# grid barrier: non-leader workgroups poll the global release generation directly instead of the per-XCD word (one hop less)
# baseline (speedup 1.0000x reference)
; __device__ __forceinline__ unsigned xb_ld(unsigned* p)              { return __hip_atomic_load(p, __ATOMIC_RELAXED, __HIP_MEMORY_SCOPE_AGENT); }
; __device__ __forceinline__ unsigned xb_add(unsigned* p, unsigned v) { return __hip_atomic_fetch_add(p, v, __ATOMIC_RELAXED, __HIP_MEMORY_SCOPE_AGENT); }
; #define XB_SPIN(cond, bar) do { unsigned _sp = 0; while (cond) { __builtin_amdgcn_s_sleep(1); \
;     if ((++_sp & 255u) == 0u) { if (xb_ld(&(bar)[XB_TMO])) break; if (_sp > XB_SPIN_CAP) { atomicAdd(&(bar)[XB_TMO], 1u); break; } } } } while (0)
; __device__ __forceinline__ void xcd_barrier(const XcdBarrier& b) {
;     ...
;         const unsigned old = xb_add(&bar[XB_XSUB(b.x)], 1u);
;         const unsigned gen = old / nloc;
;         if (old + 1u == (gen + 1u) * nloc) {
;             __builtin_amdgcn_fence(__ATOMIC_RELEASE, "agent");
;             asm volatile("s_waitcnt vmcnt(0)" ::: "memory");
;             const unsigned og = xb_add(&bar[XB_TOP], 1u);
;             const unsigned tg = og / nx;
;             if (og + 1u == (tg + 1u) * nx) xb_add(&bar[XB_TOPGEN], 1u);
;             else XB_SPIN(xb_ld(&bar[XB_TOPGEN]) == tg, bar);
;             __builtin_amdgcn_fence(__ATOMIC_ACQUIRE, "agent");
;             xb_add(&bar[XB_XGEN(b.x)], 1u);
;             asm volatile("s_waitcnt vmcnt(0)" ::: "memory");
;         } else {
;             XB_SPIN(xb_ld(&bar[XB_XGEN(b.x)]) == gen, bar);
.LBB0_222:
	s_or_b64 exec, exec, s[18:19]
	v_cvt_f32_u32_e32 v5, v3
	s_waitcnt vmcnt(0)
	v_readfirstlane_b32 s2, v4
	v_sub_u32_e32 v4, 0, v3
	v_rcp_iflag_f32_e32 v5, v5
	v_add_u32_e32 v6, s2, v2
	v_mul_f32_e32 v5, 0x4f7ffffe, v5
	v_cvt_u32_f32_e32 v5, v5
	v_mul_lo_u32 v2, v4, v5
	v_mul_hi_u32 v2, v5, v2
	v_add_u32_e32 v2, v5, v2
	v_mul_hi_u32 v2, v6, v2
	v_mul_lo_u32 v4, v2, v3
	v_sub_u32_e32 v4, v6, v4
	v_add_u32_e32 v5, 1, v2
	v_sub_u32_e32 v7, v4, v3
	v_cmp_ge_u32_e32 vcc, v4, v3
	s_nop 1
	v_cndmask_b32_e32 v2, v2, v5, vcc
	v_cndmask_b32_e32 v4, v4, v7, vcc
	v_add_u32_e32 v5, 1, v2
	v_cmp_ge_u32_e32 vcc, v4, v3
	v_add_u32_e32 v4, 1, v6
	s_nop 0
	v_cndmask_b32_e32 v2, v2, v5, vcc
	v_mul_lo_u32 v5, v3, v2
	v_add_u32_e32 v3, v5, v3
	v_cmp_ne_u32_e32 vcc, v4, v3
	s_and_saveexec_b64 s[4:5], vcc
	s_xor_b64 s[18:19], exec, s[4:5]
	s_cbranch_execz .LBB0_236
	v_readlane_b32 s4, v245, 34
	v_readlane_b32 s5, v245, 35
	s_waitcnt lgkmcnt(0)
	s_nop 3
	global_load_dword v0, v1, s[4:5] sc1
	s_waitcnt vmcnt(0)
	v_cmp_eq_u32_e32 vcc, v0, v2
	s_and_saveexec_b64 s[24:25], vcc
	s_cbranch_execz .LBB0_235
	s_mov_b32 s2, 1
	s_mov_b64 s[26:27], 0
	s_branch .LBB0_226

; __device__ __forceinline__ unsigned xb_ld(unsigned* p)              { return __hip_atomic_load(p, __ATOMIC_RELAXED, __HIP_MEMORY_SCOPE_AGENT); }
; #define XB_SPIN(cond, bar) do { unsigned _sp = 0; while (cond) { __builtin_amdgcn_s_sleep(1); \
;     if ((++_sp & 255u) == 0u) { if (xb_ld(&(bar)[XB_TMO])) break; if (_sp > XB_SPIN_CAP) { atomicAdd(&(bar)[XB_TMO], 1u); break; } } } } while (0)
; __device__ __forceinline__ void xcd_barrier(const XcdBarrier& b) {
;     ...
;             XB_SPIN(xb_ld(&bar[XB_XGEN(b.x)]) == gen, bar);
.LBB0_230:
	v_readlane_b32 s4, v245, 34
	v_readlane_b32 s5, v245, 35
	s_add_i32 s2, s2, 1
	s_mov_b64 s[40:41], -1
	s_nop 2
	global_load_dword v0, v1, s[4:5] sc1
	s_waitcnt vmcnt(0)
	v_cmp_ne_u32_e32 vcc, v0, v2
	s_orn2_b64 s[34:35], vcc, exec
	s_branch .LBB0_225

; __device__ __forceinline__ unsigned xb_ld(unsigned* p)              { return __hip_atomic_load(p, __ATOMIC_RELAXED, __HIP_MEMORY_SCOPE_AGENT); }
; __device__ __forceinline__ unsigned xb_add(unsigned* p, unsigned v) { return __hip_atomic_fetch_add(p, v, __ATOMIC_RELAXED, __HIP_MEMORY_SCOPE_AGENT); }
; #define XB_SPIN(cond, bar) do { unsigned _sp = 0; while (cond) { __builtin_amdgcn_s_sleep(1); \
;     if ((++_sp & 255u) == 0u) { if (xb_ld(&(bar)[XB_TMO])) break; if (_sp > XB_SPIN_CAP) { atomicAdd(&(bar)[XB_TMO], 1u); break; } } } } while (0)
; __device__ __forceinline__ void xcd_barrier(const XcdBarrier& b) {
;     ...
;         const unsigned old = xb_add(&bar[XB_XSUB(b.x)], 1u);
;         const unsigned gen = old / nloc;
;         if (old + 1u == (gen + 1u) * nloc) {
;             __builtin_amdgcn_fence(__ATOMIC_RELEASE, "agent");
;             asm volatile("s_waitcnt vmcnt(0)" ::: "memory");
;             const unsigned og = xb_add(&bar[XB_TOP], 1u);
;             const unsigned tg = og / nx;
;             if (og + 1u == (tg + 1u) * nx) xb_add(&bar[XB_TOPGEN], 1u);
;             else XB_SPIN(xb_ld(&bar[XB_TOPGEN]) == tg, bar);
;             __builtin_amdgcn_fence(__ATOMIC_ACQUIRE, "agent");
;             xb_add(&bar[XB_XGEN(b.x)], 1u);
;             asm volatile("s_waitcnt vmcnt(0)" ::: "memory");
;         } else {
;             XB_SPIN(xb_ld(&bar[XB_XGEN(b.x)]) == gen, bar);
.LBB0_290:
	s_or_b64 exec, exec, s[18:19]
	v_cvt_f32_u32_e32 v5, v3
	s_waitcnt vmcnt(0)
	v_readfirstlane_b32 s2, v4
	v_sub_u32_e32 v4, 0, v3
	v_rcp_iflag_f32_e32 v5, v5
	v_add_u32_e32 v6, s2, v0
	v_mul_f32_e32 v5, 0x4f7ffffe, v5
	v_cvt_u32_f32_e32 v5, v5
	v_mul_lo_u32 v0, v4, v5
	v_mul_hi_u32 v0, v5, v0
	v_add_u32_e32 v0, v5, v0
	v_mul_hi_u32 v0, v6, v0
	v_mul_lo_u32 v4, v0, v3
	v_sub_u32_e32 v4, v6, v4
	v_add_u32_e32 v5, 1, v0
	v_cmp_ge_u32_e32 vcc, v4, v3
	s_nop 1
	v_cndmask_b32_e32 v0, v0, v5, vcc
	v_sub_u32_e32 v5, v4, v3
	v_cndmask_b32_e32 v4, v4, v5, vcc
	v_add_u32_e32 v5, 1, v0
	v_cmp_ge_u32_e32 vcc, v4, v3
	v_add_u32_e32 v4, 1, v6
	s_nop 0
	v_cndmask_b32_e32 v0, v0, v5, vcc
	v_mul_lo_u32 v5, v3, v0
	v_add_u32_e32 v3, v5, v3
	v_cmp_ne_u32_e32 vcc, v4, v3
	s_and_saveexec_b64 s[4:5], vcc
	s_xor_b64 s[18:19], exec, s[4:5]
	s_cbranch_execz .LBB0_304
	v_readlane_b32 s4, v245, 34
	v_readlane_b32 s5, v245, 35
	s_waitcnt lgkmcnt(0)
	s_nop 3
	global_load_dword v2, v1, s[4:5] sc1
	s_waitcnt vmcnt(0)
	v_cmp_eq_u32_e32 vcc, v2, v0
	s_and_saveexec_b64 s[24:25], vcc
	s_cbranch_execz .LBB0_303
	s_mov_b32 s2, 1
	s_mov_b64 s[26:27], 0
	s_branch .LBB0_294

; __device__ __forceinline__ unsigned xb_ld(unsigned* p)              { return __hip_atomic_load(p, __ATOMIC_RELAXED, __HIP_MEMORY_SCOPE_AGENT); }
; __device__ __forceinline__ unsigned xb_add(unsigned* p, unsigned v) { return __hip_atomic_fetch_add(p, v, __ATOMIC_RELAXED, __HIP_MEMORY_SCOPE_AGENT); }
; #define XB_SPIN(cond, bar) do { unsigned _sp = 0; while (cond) { __builtin_amdgcn_s_sleep(1); \
;     if ((++_sp & 255u) == 0u) { if (xb_ld(&(bar)[XB_TMO])) break; if (_sp > XB_SPIN_CAP) { atomicAdd(&(bar)[XB_TMO], 1u); break; } } } } while (0)
; __device__ __forceinline__ void xcd_barrier(const XcdBarrier& b) {
;     ...
;         const unsigned old = xb_add(&bar[XB_XSUB(b.x)], 1u);
;         const unsigned gen = old / nloc;
;         if (old + 1u == (gen + 1u) * nloc) {
;             __builtin_amdgcn_fence(__ATOMIC_RELEASE, "agent");
;             asm volatile("s_waitcnt vmcnt(0)" ::: "memory");
;             const unsigned og = xb_add(&bar[XB_TOP], 1u);
;             const unsigned tg = og / nx;
;             if (og + 1u == (tg + 1u) * nx) xb_add(&bar[XB_TOPGEN], 1u);
;             else XB_SPIN(xb_ld(&bar[XB_TOPGEN]) == tg, bar);
;             __builtin_amdgcn_fence(__ATOMIC_ACQUIRE, "agent");
;             xb_add(&bar[XB_XGEN(b.x)], 1u);
;             asm volatile("s_waitcnt vmcnt(0)" ::: "memory");
;         } else {
;             XB_SPIN(xb_ld(&bar[XB_XGEN(b.x)]) == gen, bar);
.LBB0_940:
	s_or_b64 exec, exec, s[16:17]
	v_cvt_f32_u32_e32 v5, v3
	s_waitcnt vmcnt(0)
	v_readfirstlane_b32 s2, v4
	v_sub_u32_e32 v4, 0, v3
	v_rcp_iflag_f32_e32 v5, v5
	v_add_u32_e32 v6, s2, v0
	v_mul_f32_e32 v5, 0x4f7ffffe, v5
	v_cvt_u32_f32_e32 v5, v5
	v_mul_lo_u32 v0, v4, v5
	v_mul_hi_u32 v0, v5, v0
	v_add_u32_e32 v0, v5, v0
	v_mul_hi_u32 v0, v6, v0
	v_mul_lo_u32 v4, v0, v3
	v_sub_u32_e32 v4, v6, v4
	v_add_u32_e32 v5, 1, v0
	v_cmp_ge_u32_e32 vcc, v4, v3
	s_nop 1
	v_cndmask_b32_e32 v0, v0, v5, vcc
	v_sub_u32_e32 v5, v4, v3
	v_cndmask_b32_e32 v4, v4, v5, vcc
	v_add_u32_e32 v5, 1, v0
	v_cmp_ge_u32_e32 vcc, v4, v3
	v_add_u32_e32 v4, 1, v6
	s_nop 0
	v_cndmask_b32_e32 v0, v0, v5, vcc
	v_mul_lo_u32 v5, v3, v0
	v_add_u32_e32 v3, v5, v3
	v_cmp_ne_u32_e32 vcc, v4, v3
	s_and_saveexec_b64 s[4:5], vcc
	s_xor_b64 s[16:17], exec, s[4:5]
	s_cbranch_execz .LBB0_954
	v_readlane_b32 s4, v245, 34
	v_readlane_b32 s5, v245, 35
	s_waitcnt lgkmcnt(0)
	s_nop 3
	global_load_dword v2, v1, s[4:5] sc1
	s_waitcnt vmcnt(0)
	v_cmp_eq_u32_e32 vcc, v2, v0
	s_and_saveexec_b64 s[18:19], vcc
	s_cbranch_execz .LBB0_953
	s_mov_b32 s2, 1
	s_mov_b64 s[22:23], 0
	s_branch .LBB0_944
